# attention phase: static s_setprio 1 for waves 0-3 instead of 4-7 (per-half A/B of the priority lever)
# speedup vs baseline: 1.0058x; 1.0058x over previous
; __device__ __forceinline__ void attn_unit(int b, int qb, int kvh, const bf16_t* __restrict__ QP, const bf16_t* __restrict__ KP, const bf16_t* __restrict__ VT, const float* sink, bf16_t* MIX, unsigned char* ldsb, int tid, int wave, int lane) {
;     const int fr = lane & 15, fq = lane >> 4, hq = kvh * 4 + (wave >> 1), q0 = qb * 64 + (wave & 1) * 32;
; __global__ void __launch_bounds__(512, 2) fwd_megakernel(Args args) {
;     ...
;     { const Ctx X = mkctx(lds); for (int u = X.bx; u < 1024; u += X.G) attn_unit(u >> 7, (u >> 1) & 63, u & 1, QP, KP, VT, args.in[13], MIX, lds, X.tid, X.wave, X.lane); }
.Lat_adv_11:
	v_readfirstlane_b32 s0, v206
	s_nop 3
	s_lshr_b32 s0, s0, 6
	s_cmp_ge_u32 s0, 4
	s_cbranch_scc1 .Lat_prio_done
	s_setprio 1
